# in-proj GEMM LDS relayout: 8-row x 128-B sub-tiles (whole-line LDS-DMA pieces), XOR-by-row chunk swizzle, two fragment-read bases
# speedup vs baseline: 1.0080x; 1.0080x over previous
; #define LAS __attribute__((address_space(3)))
; #define PG8_STAGE(bufoff, gbase, voff) do { _Pragma("unroll") for (int _i = 0; _i < 2; ++_i) \
;         __builtin_amdgcn_global_load_lds((const unsigned*)((const char*)(gbase) + (voff)[_i]), (LAS unsigned*)(lds + (bufoff) + ldsw + _i * 8192), 16, 0, 0); } while (0)
;     __device__ bool next(int i, Unit& u) const {
;         const long L = (long)i * G + c; if (L >= nwg) return false;
;         int wgid = (int)L; { const int q = nwg / NXCD, r = nwg % NXCD, xcd = wgid % NXCD, off = wgid / NXCD; wgid = (xcd < r ? xcd * (q + 1) : r * (q + 1) + (xcd - r) * q) + off; }
;         const int nig = WGM * nN, gid = wgid / nig, fm = gid * WGM, gsz = (nM - fm) < WGM ? (nM - fm) : WGM;
;         u.pm = fm + ((wgid % nig) % gsz); u.pn = (wgid % nig) / gsz; return true;
;     }
; template <class Epi>
; __device__ __forceinline__ void gemm_phase(LAS unsigned char* lds, const Gemm g, const StaticOrder& S, const Epi& E, const int tid) {
;     const int wid = __builtin_amdgcn_readfirstlane(tid >> 6), lane = tid & 63, wr = wid >> 2, wc = wid & 3, fr = lane & 15, fq = lane >> 4;
;     const int K = g.K, nt = K / BK;
;     unsigned voffA[2], voffB[2];
; #pragma unroll
;     for (int i = 0; i < 2; ++i) { int R, C; stage_rc(tid * 16 + i * 8192, R, C); const int Rb = Epi::BJ_ADJ ? ((R >> 5) * 64 + perm32(R & 31)) : (Epi::PERM ? ((R & ~31) + perm32(R & 31)) : R);
;         voffA[i] = (unsigned)(R * K + C) * 2u; voffB[i] = (unsigned)(Rb * K + C) * 2u; }
;     const size_t kstep = (size_t)(BK * 2);
;     const size_t hstep = (size_t)HALF * K * 2;
;     const size_t tstep = 2 * hstep;
;     const size_t hstepB = Epi::BJ_ADJ ? (size_t)32 * K * 2 : hstep;
;     const unsigned ldsw = (unsigned)wid * 1024u;
;     const int aoff = lds_byte(wr * 64 + fr, fq * 8), boff = lds_byte(wc * 32 + fr, fq * 8);
;     ...
;     const char* cA = (const char*)g.A + (size_t)cur.pm * tstep; const char* cB = (const char*)g.Bt + (size_t)cur.pn * tstep;
;     PG8_STAGE(PG8_SB(0, 0), cB, voffB); PG8_STAGE(PG8_SA(0, 0), cA, voffA); PG8_STAGE(PG8_SB(0, 1), cB + hstepB, voffB); PG8_STAGE(PG8_SA(0, 1), cA + hstep, voffA);
;     if (wr == 1) PG8_BAR;
;     PG8_WAIT_V(4); PG8_BAR;
;     PG8_STAGE(PG8_SB(1, 0), cB + kstep, voffB); PG8_STAGE(PG8_SA(1, 0), cA + kstep, voffA); PG8_STAGE(PG8_SB(1, 1), cB + hstepB + kstep, voffB);
;     PG8_WAIT_V(6); PG8_BAR;
.LBB0_324:
	s_andn2_b64 vcc, exec, s[0:1]
	s_cbranch_vccnz .LBB0_337
	v_readlane_b32 s0, v253, 15
	v_readlane_b32 s1, v253, 16
	s_andn2_b64 vcc, exec, s[0:1]
	v_readfirstlane_b32 s20, v72
	s_cbranch_vccnz .LBB0_337
	v_lshlrev_b32_e32 v1, 4, v72
	v_add_u32_e32 v0, 0x2000, v1
	v_ashrrev_i32_e32 v2, 31, v0
	v_lshrrev_b32_e32 v2, 22, v2
	v_add_u32_e32 v2, v0, v2
	v_ashrrev_i32_e32 v4, 10, v2
	v_mul_i32_i24_e32 v2, 0x400, v4
	v_sub_u32_e32 v0, v0, v2
	v_lshrrev_b32_e32 v2, 4, v0
	v_bitop3_b32 v0, v2, v0, 32 bitop3:0x6c
	v_ashrrev_i32_e32 v2, 31, v0
	v_lshrrev_b32_e32 v2, 26, v2
	v_add_u32_e32 v2, v0, v2
	v_lshlrev_b32_e32 v7, 3, v4
	v_ashrrev_i32_e32 v5, 6, v2
	v_and_b32_e32 v7, -16, v7
	v_add_u32_e32 v7, v5, v7
	v_lshrrev_b32_e32 v8, 2, v7
	v_lshlrev_b32_e32 v9, 1, v7
	v_and_b32_e32 v2, 0xc0, v2
	v_and_b32_e32 v6, 3, v5
	v_and_b32_e32 v8, 4, v8
	v_and_b32_e32 v9, 0xfffd8, v9
	v_sub_u32_e32 v0, v0, v2
	v_or3_b32 v8, v6, v8, v9
	v_lshlrev_b32_e32 v6, 5, v4
	v_ashrrev_i16_sdwa v0, v183, sext(v0) dst_sel:DWORD dst_unused:UNUSED_PAD src0_sel:DWORD src1_sel:BYTE_0
	v_and_b32_e32 v9, 32, v6
	v_bfe_i32 v6, v0, 0, 16
	v_add_lshl_u32 v2, v9, v6, 1
	v_lshl_add_u32 v0, v8, 12, v2
	v_lshl_add_u32 v132, v7, 12, v2
	v_bfe_i32 v2, v72, 27, 1
	v_lshrrev_b32_e32 v2, 22, v2
	v_add_u32_e32 v2, v1, v2
	v_and_b32_e32 v2, 0xfffffc00, v2
	v_sub_u32_e32 v1, v1, v2
	v_lshrrev_b32_e32 v2, 4, v1
	v_ashrrev_i32_e32 v8, 31, v72
	v_bitop3_b32 v1, v2, v1, 32 bitop3:0x6c
	v_lshrrev_b32_e32 v8, 26, v8
	v_ashrrev_i32_e32 v2, 31, v1
	v_add_u32_e32 v8, v72, v8
	v_lshrrev_b32_e32 v2, 26, v2
	v_ashrrev_i32_e32 v8, 6, v8
	v_add_u32_e32 v2, v1, v2
	v_lshlrev_b32_e32 v10, 3, v8
	v_ashrrev_i32_e32 v7, 6, v2
	v_and_b32_e32 v10, -16, v10
	s_mul_i32 s0, s22, 0x3c00000
	v_add_u32_e32 v10, v7, v10
	s_add_u32 s24, s66, s0
	v_lshrrev_b32_e32 v11, 2, v10
	v_lshlrev_b32_e32 v12, 1, v10
	v_and_b32_e32 v2, 0xc0, v2
	s_addc_u32 s25, s67, 0
	s_ashr_i32 s1, s20, 6
	v_and_b32_e32 v9, 3, v7
	v_and_b32_e32 v11, 4, v11
	v_and_b32_e32 v12, 0xfffd8, v12
	v_sub_u32_e32 v1, v1, v2
	s_ashr_i32 s0, s20, 8
	s_lshl_b32 s38, s1, 10
	v_or3_b32 v11, v9, v11, v12
	v_lshlrev_b32_e32 v9, 5, v8
	v_ashrrev_i16_sdwa v1, v183, sext(v1) dst_sel:DWORD dst_unused:UNUSED_PAD src0_sel:DWORD src1_sel:BYTE_0
	v_readlane_b32 s4, v253, 31
	v_and_b32_e32 v12, 32, v9
	v_bfe_i32 v9, v1, 0, 16
	v_readlane_b32 s5, v253, 32
	s_add_u32 s18, s24, s4
	v_add_lshl_u32 v1, v12, v9, 1
	s_addc_u32 s19, s25, s5
	s_add_i32 s39, s38, 0
	v_lshl_add_u32 v2, v11, 12, v1
	v_and_b32_e32 v245, 63, v72
	v_lshrrev_b32_e32 v246, 3, v245
	v_and_b32_e32 v247, 7, v245
	v_xor_b32_e32 v247, v247, v246
	v_lshlrev_b32_e32 v247, 4, v247
	v_lshl_add_u32 v246, s1, 3, v246
	v_bfe_u32 v248, v246, 2, 2
	v_lshlrev_b32_e32 v248, 3, v248
	v_bfe_u32 v249, v246, 4, 1
	v_lshl_or_b32 v248, v249, 2, v248
	v_and_b32_e32 v249, 3, v246
	v_or_b32_e32 v248, v248, v249
	v_lshrrev_b32_e32 v249, 5, v246
	v_lshl_or_b32 v248, v249, 6, v248
	v_lshl_add_u32 v2, v248, 12, v247
	v_add_u32_e32 v0, 0x80000, v2
	s_add_i32 m0, s39, 0x10000
	v_readlane_b32 s4, v253, 35
	global_load_lds_dwordx4 v2, s[18:19]
	s_add_i32 m0, s39, 0x12000
	v_lshl_add_u32 v134, v10, 12, v1
	v_mov_b32_e32 v243, v134
	v_mov_b32_e32 v244, v132
	v_lshl_add_u32 v134, v246, 12, v247
	v_add_u32_e32 v132, 0x40000, v134
	global_load_lds_dwordx4 v0, s[18:19]
	s_mov_b32 m0, s39
	v_readlane_b32 s5, v253, 36
	s_add_i32 s40, s39, 0x2000
	s_nop 3
	global_load_lds_dwordx4 v134, s[4:5]
	s_mov_b32 m0, s40
	s_nop 0
	global_load_lds_dwordx4 v132, s[4:5]
	s_add_u32 s4, s18, 0x20000
	s_addc_u32 s5, s19, 0
	s_add_i32 m0, s39, 0x14000
	s_add_i32 s41, s39, 0x4000
	global_load_lds_dwordx4 v2, s[4:5]
	s_add_i32 m0, s39, 0x16000
	s_add_i32 s42, s39, 0x6000
	global_load_lds_dwordx4 v0, s[4:5]
	v_readlane_b32 s4, v253, 37
	s_mov_b32 m0, s41
	v_readlane_b32 s5, v253, 38
	s_cmp_lg_u32 s0, 1
	s_nop 3
	global_load_lds_dwordx4 v134, s[4:5]
	s_mov_b32 m0, s42
	s_nop 0
	global_load_lds_dwordx4 v132, s[4:5]
	s_cbranch_scc1 .LBB0_328
	s_barrier
.LBB0_328:
	v_lshl_add_u64 v[10:11], s[18:19], 0, v[2:3]
	v_mov_b32_e32 v1, v3
	v_readlane_b32 s14, v253, 35
	v_lshl_add_u64 v[12:13], s[18:19], 0, v[0:1]
	v_mov_b32_e32 v135, v3
	v_readlane_b32 s15, v253, 36
	s_and_b32 s1, s1, 3
	s_add_i32 m0, s39, 0x18000
	v_lshl_add_u64 v[10:11], v[10:11], 0, s[30:31]
	v_lshl_add_u64 v[14:15], s[14:15], 0, v[134:135]
	v_mov_b32_e32 v133, v3
	s_lshl_b32 s6, s0, 13
	s_lshl_b32 s7, s1, 12
	s_waitcnt vmcnt(4)
	s_barrier
	global_load_lds_dwordx4 v[10:11], off
	v_lshl_add_u64 v[10:11], v[12:13], 0, s[30:31]
	s_add_i32 m0, s39, 0x1a000
	s_add_i32 s43, s39, 0x8000
	s_add_i32 s46, s39, 0xa000
	v_lshl_add_u64 v[16:17], s[14:15], 0, v[132:133]
	global_load_lds_dwordx4 v[10:11], off
	v_lshl_add_u64 v[10:11], v[14:15], 0, s[30:31]
	s_mov_b32 m0, s43
	s_add_u32 s4, s18, 0x20080
	global_load_lds_dwordx4 v[10:11], off
	v_lshl_add_u64 v[10:11], v[16:17], 0, s[30:31]
	s_mov_b32 m0, s46
	s_addc_u32 s5, s19, 0
	global_load_lds_dwordx4 v[10:11], off
	s_add_i32 m0, s39, 0x1c000
	v_lshl_add_u64 v[10:11], s[4:5], 0, v[2:3]
	global_load_lds_dwordx4 v[10:11], off
	v_lshl_add_u64 v[10:11], s[4:5], 0, v[0:1]
	s_add_i32 m0, s39, 0x1e000
	v_lshlrev_b32_e32 v13, 2, v72
	global_load_lds_dwordx4 v[10:11], off
	v_lshrrev_b32_e32 v11, 1, v72
	v_and_b32_e32 v11, 24, v11
	v_and_b32_e32 v10, 15, v72
	v_lshlrev_b32_e32 v12, 1, v11
	v_lshl_or_b32 v12, v10, 6, v12
	v_and_b32_e32 v13, 32, v13
	v_bitop3_b32 v14, v12, s6, v13 bitop3:0xde
	v_bitop3_b32 v140, s7, v12, v13 bitop3:0xf6
	v_and_b32_e32 v12, 7, v72
	v_cmp_lt_u32_e64 s[4:5], 7, v10
	v_lshl_or_b32 v141, s0, 6, v12
	s_lshl_b32 s0, s1, 6
	v_cndmask_b32_e64 v10, 0, 32, s[4:5]
	v_or3_b32 v142, s0, v10, v11
	v_lshlrev_b32_e32 v10, 15, v8
	v_and_b32_e32 v10, 0xffff0000, v10
	v_lshl_add_u32 v7, v7, 12, v10
	v_and_b32_e32 v8, 1, v8
	v_lshl_or_b32 v7, v8, 6, v7
	v_lshl_add_u32 v136, v9, 1, v7
	v_sub_u32_e32 v136, v136, v243
	v_add_u32_e32 v136, v136, v134
	v_lshlrev_b32_e32 v7, 15, v4
	v_and_b32_e32 v7, 0xffff0000, v7
	s_waitcnt vmcnt(6)
	v_lshl_add_u32 v5, v5, 12, v7
	v_and_b32_e32 v4, 1, v4
	v_lshl_or_b32 v4, v4, 6, v5
	v_readlane_b32 s0, v253, 33
	s_mov_b32 s47, 0
	v_mov_b32_e32 v137, v3
	v_lshl_add_u32 v138, v6, 1, v4
	v_sub_u32_e32 v138, v138, v244
	v_add_u32_e32 v138, v138, v132
	v_mov_b32_e32 v139, v3
	v_add_u32_e32 v143, 0, v14
	v_and_b32_e32 v245, 7, v72
	v_bfe_u32 v246, v72, 3, 1
	v_bfe_u32 v247, v72, 4, 2
	v_xor_b32_e32 v248, v247, v245
	v_lshlrev_b32_e32 v248, 4, v248
	v_lshl_or_b32 v248, v245, 7, v248
	v_lshl_or_b32 v248, v246, 10, v248
	v_xor_b32_e32 v249, 64, v248
	v_add_u32_e32 v143, s6, v248
	v_add_u32_e32 v240, s6, v249
	v_add_u32_e32 v140, s7, v248
	v_add_u32_e32 v241, s7, v249
	v_readlane_b32 s48, v253, 30
	s_mov_b32 s49, s0
	s_barrier
	v_readlane_b32 s1, v253, 34

; #define PG8_STAGE(bufoff, gbase, voff) do { _Pragma("unroll") for (int _i = 0; _i < 2; ++_i) \
;         __builtin_amdgcn_global_load_lds((const unsigned*)((const char*)(gbase) + (voff)[_i]), (LAS unsigned*)(lds + (bufoff) + ldsw + _i * 8192), 16, 0, 0); } while (0)
; #define PG8_LDA(dst, b, h) do { _Pragma("unroll") for (int m = 0; m < 4; ++m) _Pragma("unroll") for (int k = 0; k < 2; ++k) dst[m][k] = *(const LAS h8*)(lds + PG8_SA(b, h) + aoff + m * 2048 + k * 1024); } while (0)
; #define PG8_LDB(dst, b, h) do { _Pragma("unroll") for (int n = 0; n < 2; ++n) _Pragma("unroll") for (int k = 0; k < 2; ++k) dst[n][k] = *(const LAS h8*)(lds + PG8_SB(b, h) + boff + n * 2048 + k * 1024); } while (0)
; #define PG8_WAIT_V(n) asm volatile("s_waitcnt vmcnt(" #n ")" ::: "memory")
; #define PG8_WAIT_L(n) asm volatile("s_waitcnt lgkmcnt(" #n ")" ::: "memory")
; #define PG8_BAR __builtin_amdgcn_s_barrier()
; #define PG8_SCHED __builtin_amdgcn_sched_barrier(0)
; template <class Epi>
; __device__ __forceinline__ void gemm_phase(LAS unsigned char* lds, const Gemm g, const StaticOrder& S, const Epi& E, const int tid) {
;     ...
;             PG8_LDB(B0, 0, 0); PG8_SCHED; PG8_LDA(At, 0, 0); PG8_STAGE(PG8_SA(1, 1), a1 + hstep, voffA);
;             PG8_WAIT_L(8); PG8_BAR; PG8_WAIT_L(0); PG8_MMA(0, 0, At, B0); PG8_BAR; PG8_SCHED;
;             PG8_LDB(B1, 0, 1); PG8_STAGE(PG8_SB(0, 0), b2, voffB);
;             PG8_BAR; PG8_WAIT_L(0); PG8_MMA(0, 1, At, B1); PG8_BAR;
;             PG8_LDA(At, 0, 1); PG8_STAGE(PG8_SA(0, 0), a2, voffA);
;             PG8_BAR; PG8_WAIT_L(0); PG8_MMA(1, 0, At, B0); PG8_BAR; PG8_SCHED;
;             PG8_STAGE(PG8_SB(0, 1), b2 + hstepB, voffB);
;             PG8_WAIT_V(6); PG8_BAR; PG8_MMA(1, 1, At, B1); PG8_BAR;
.LBB0_332:
	s_add_u32 s18, s14, 0xfff80080
	s_addc_u32 s19, s15, -1
	s_add_i32 s55, 0, 0x10000
	v_add_u32_e32 v157, s55, v140
	v_add_u32_e32 v242, s55, v241
	ds_read_b128 v[144:147], v157
	ds_read_b128 v[162:165], v242
	ds_read_b128 v[166:169], v157 offset:2048
	ds_read_b128 v[170:173], v242 offset:2048
	s_cmp_eq_u32 s54, 28
	s_cselect_b32 s23, s9, s19
	s_cselect_b32 s22, s50, s18
	s_cselect_b32 s19, s1, s53
	s_cselect_b32 s18, s51, s52
	v_lshl_add_u64 v[178:179], s[14:15], 0, v[136:137]
	s_add_i32 m0, s39, 0xc000
	ds_read_b128 v[174:177], v143
	ds_read_b128 v[190:193], v240
	ds_read_b128 v[194:197], v143 offset:2048
	ds_read_b128 v[198:201], v240 offset:2048
	ds_read_b128 v[202:205], v143 offset:4096
	ds_read_b128 v[206:209], v240 offset:4096
	ds_read_b128 v[210:213], v143 offset:6144
	ds_read_b128 v[214:217], v240 offset:6144
	global_load_lds_dwordx4 v[178:179], off
	v_lshl_add_u64 v[178:179], s[14:15], 0, v[138:139]
	s_add_i32 m0, s39, 0xe000
	s_nop 0
	global_load_lds_dwordx4 v[178:179], off
	s_waitcnt lgkmcnt(8)
	s_barrier
	s_waitcnt lgkmcnt(0)
	s_waitcnt lgkmcnt(0)
	v_mfma_f32_16x16x32_bf16 v[124:127], v[144:147], v[174:177], v[124:127]
	v_mfma_f32_16x16x32_bf16 v[128:131], v[166:169], v[174:177], v[128:131]
	v_mfma_f32_16x16x32_bf16 v[108:111], v[144:147], v[194:197], v[108:111]
	v_mfma_f32_16x16x32_bf16 v[112:115], v[166:169], v[194:197], v[112:115]
	v_mfma_f32_16x16x32_bf16 v[92:95], v[144:147], v[202:205], v[92:95]
	v_mfma_f32_16x16x32_bf16 v[96:99], v[166:169], v[202:205], v[96:99]
	v_mfma_f32_16x16x32_bf16 v[76:79], v[144:147], v[210:213], v[76:79]
	v_mfma_f32_16x16x32_bf16 v[80:83], v[166:169], v[210:213], v[80:83]
	v_mfma_f32_16x16x32_bf16 v[124:127], v[162:165], v[190:193], v[124:127]
	v_mfma_f32_16x16x32_bf16 v[128:131], v[170:173], v[190:193], v[128:131]
	v_mfma_f32_16x16x32_bf16 v[108:111], v[162:165], v[198:201], v[108:111]
	v_mfma_f32_16x16x32_bf16 v[112:115], v[170:173], v[198:201], v[112:115]
	v_mfma_f32_16x16x32_bf16 v[92:95], v[162:165], v[206:209], v[92:95]
	v_mfma_f32_16x16x32_bf16 v[96:99], v[170:173], v[206:209], v[96:99]
	v_mfma_f32_16x16x32_bf16 v[76:79], v[162:165], v[214:217], v[76:79]
	v_mfma_f32_16x16x32_bf16 v[80:83], v[170:173], v[214:217], v[80:83]
	s_barrier
	s_add_i32 s58, 0, 0x14000
	s_add_i32 s55, s55, s38
	v_add_u32_e32 v157, s58, v140
	v_add_u32_e32 v242, s58, v241
	v_lshl_add_u64 v[178:179], s[18:19], 0, v[2:3]
	s_mov_b32 m0, s55
	ds_read_b128 v[218:221], v157
	ds_read_b128 v[222:225], v242
	ds_read_b128 v[226:229], v157 offset:2048
	ds_read_b128 v[230:233], v242 offset:2048
	global_load_lds_dwordx4 v[178:179], off
	v_lshl_add_u64 v[234:235], s[18:19], 0, v[0:1]
	s_add_i32 m0, s55, 0x2000
	s_nop 0
	global_load_lds_dwordx4 v[234:235], off
	s_barrier
	s_waitcnt lgkmcnt(0)
	s_waitcnt lgkmcnt(0)
	v_mfma_f32_16x16x32_bf16 v[116:119], v[218:221], v[174:177], v[116:119]
	v_mfma_f32_16x16x32_bf16 v[120:123], v[226:229], v[174:177], v[120:123]
	v_mfma_f32_16x16x32_bf16 v[100:103], v[218:221], v[194:197], v[100:103]
	v_mfma_f32_16x16x32_bf16 v[104:107], v[226:229], v[194:197], v[104:107]
	v_mfma_f32_16x16x32_bf16 v[84:87], v[218:221], v[202:205], v[84:87]
	v_mfma_f32_16x16x32_bf16 v[88:91], v[226:229], v[202:205], v[88:91]
	v_mfma_f32_16x16x32_bf16 v[68:71], v[218:221], v[210:213], v[68:71]
	v_mfma_f32_16x16x32_bf16 v[72:75], v[226:229], v[210:213], v[72:75]
	v_mfma_f32_16x16x32_bf16 v[116:119], v[222:225], v[190:193], v[116:119]
	v_mfma_f32_16x16x32_bf16 v[120:123], v[230:233], v[190:193], v[120:123]
	v_mfma_f32_16x16x32_bf16 v[100:103], v[222:225], v[198:201], v[100:103]
	v_mfma_f32_16x16x32_bf16 v[104:107], v[230:233], v[198:201], v[104:107]
	v_mfma_f32_16x16x32_bf16 v[84:87], v[222:225], v[206:209], v[84:87]
	v_mfma_f32_16x16x32_bf16 v[88:91], v[230:233], v[206:209], v[88:91]
	v_mfma_f32_16x16x32_bf16 v[68:71], v[222:225], v[214:217], v[68:71]
	v_mfma_f32_16x16x32_bf16 v[72:75], v[230:233], v[214:217], v[72:75]
	s_mov_b32 m0, s39
	v_lshl_add_u64 v[236:237], s[22:23], 0, v[134:135]
	s_barrier
	ds_read_b128 v[174:177], v143 offset:16384
	ds_read_b128 v[190:193], v240 offset:16384
	ds_read_b128 v[194:197], v143 offset:18432
	ds_read_b128 v[198:201], v240 offset:18432
	ds_read_b128 v[202:205], v143 offset:20480
	ds_read_b128 v[206:209], v240 offset:20480
	ds_read_b128 v[210:213], v143 offset:22528
	ds_read_b128 v[214:217], v240 offset:22528
	global_load_lds_dwordx4 v[236:237], off
	v_lshl_add_u64 v[238:239], s[22:23], 0, v[132:133]
	s_mov_b32 m0, s40
	s_nop 0
	global_load_lds_dwordx4 v[238:239], off
	s_barrier
	s_waitcnt lgkmcnt(0)
	s_waitcnt lgkmcnt(0)
	v_mfma_f32_16x16x32_bf16 v[60:63], v[144:147], v[174:177], v[60:63]
	v_mfma_f32_16x16x32_bf16 v[64:67], v[166:169], v[174:177], v[64:67]
	v_mfma_f32_16x16x32_bf16 v[44:47], v[144:147], v[194:197], v[44:47]
	v_mfma_f32_16x16x32_bf16 v[48:51], v[166:169], v[194:197], v[48:51]
	v_mfma_f32_16x16x32_bf16 v[28:31], v[144:147], v[202:205], v[28:31]
	v_mfma_f32_16x16x32_bf16 v[32:35], v[166:169], v[202:205], v[32:35]
	v_mfma_f32_16x16x32_bf16 v[12:15], v[144:147], v[210:213], v[12:15]
	v_mfma_f32_16x16x32_bf16 v[16:19], v[166:169], v[210:213], v[16:19]
	v_mfma_f32_16x16x32_bf16 v[60:63], v[162:165], v[190:193], v[60:63]
	v_mfma_f32_16x16x32_bf16 v[64:67], v[170:173], v[190:193], v[64:67]
	v_mfma_f32_16x16x32_bf16 v[44:47], v[162:165], v[198:201], v[44:47]
	v_mfma_f32_16x16x32_bf16 v[48:51], v[170:173], v[198:201], v[48:51]
	v_mfma_f32_16x16x32_bf16 v[28:31], v[162:165], v[206:209], v[28:31]
	v_mfma_f32_16x16x32_bf16 v[32:35], v[170:173], v[206:209], v[32:35]
	v_mfma_f32_16x16x32_bf16 v[12:15], v[162:165], v[214:217], v[12:15]
	v_mfma_f32_16x16x32_bf16 v[16:19], v[170:173], v[214:217], v[16:19]
	s_barrier
; #define PG8_STAGE(bufoff, gbase, voff) do { _Pragma("unroll") for (int _i = 0; _i < 2; ++_i) \
;         __builtin_amdgcn_global_load_lds((const unsigned*)((const char*)(gbase) + (voff)[_i]), (LAS unsigned*)(lds + (bufoff) + ldsw + _i * 8192), 16, 0, 0); } while (0)
; #define PG8_LDA(dst, b, h) do { _Pragma("unroll") for (int m = 0; m < 4; ++m) _Pragma("unroll") for (int k = 0; k < 2; ++k) dst[m][k] = *(const LAS h8*)(lds + PG8_SA(b, h) + aoff + m * 2048 + k * 1024); } while (0)
; #define PG8_LDB(dst, b, h) do { _Pragma("unroll") for (int n = 0; n < 2; ++n) _Pragma("unroll") for (int k = 0; k < 2; ++k) dst[n][k] = *(const LAS h8*)(lds + PG8_SB(b, h) + boff + n * 2048 + k * 1024); } while (0)
; #define PG8_WAIT_V(n) asm volatile("s_waitcnt vmcnt(" #n ")" ::: "memory")
; #define PG8_WAIT_L(n) asm volatile("s_waitcnt lgkmcnt(" #n ")" ::: "memory")
; #define PG8_BAR __builtin_amdgcn_s_barrier()
; #define PG8_SCHED __builtin_amdgcn_sched_barrier(0)
; template <class Epi>
; __device__ __forceinline__ void gemm_phase(LAS unsigned char* lds, const Gemm g, const StaticOrder& S, const Epi& E, const int tid) {
;     ...
;             PG8_WAIT_V(6); PG8_BAR; PG8_MMA(1, 1, At, B1); PG8_BAR;
;             PG8_LDB(B0, 1, 0); PG8_SCHED; PG8_LDA(At, 1, 0); PG8_STAGE(PG8_SA(0, 1), a2 + hstep, voffA);
;             PG8_WAIT_L(8); PG8_BAR; PG8_WAIT_L(0); PG8_MMA(0, 0, At, B0); PG8_BAR; PG8_SCHED;
;             PG8_LDB(B1, 1, 1); PG8_STAGE(PG8_SB(1, 0), b3, voffB);
;             PG8_BAR; PG8_WAIT_L(0); PG8_MMA(0, 1, At, B1); PG8_BAR;
;             PG8_LDA(At, 1, 1); PG8_STAGE(PG8_SA(1, 0), a3, voffA);
	s_add_u32 s56, s18, 0x20000
	s_addc_u32 s57, s19, 0
	s_add_i32 s55, s58, s38
	v_lshl_add_u64 v[144:145], s[56:57], 0, v[2:3]
	s_mov_b32 m0, s55
	s_nop 0
	global_load_lds_dwordx4 v[144:145], off
	v_lshl_add_u64 v[144:145], s[56:57], 0, v[0:1]
	s_add_i32 m0, s55, 0x2000
	s_nop 0
	global_load_lds_dwordx4 v[144:145], off
	s_waitcnt vmcnt(6)
	s_barrier
	v_mfma_f32_16x16x32_bf16 v[52:55], v[218:221], v[174:177], v[52:55]
	v_mfma_f32_16x16x32_bf16 v[56:59], v[226:229], v[174:177], v[56:59]
	v_mfma_f32_16x16x32_bf16 v[36:39], v[218:221], v[194:197], v[36:39]
	v_mfma_f32_16x16x32_bf16 v[40:43], v[226:229], v[194:197], v[40:43]
	v_mfma_f32_16x16x32_bf16 v[20:23], v[218:221], v[202:205], v[20:23]
	v_mfma_f32_16x16x32_bf16 v[24:27], v[226:229], v[202:205], v[24:27]
	v_mfma_f32_16x16x32_bf16 v[8:11], v[218:221], v[210:213], v[8:11]
	v_mfma_f32_16x16x32_bf16 v[4:7], v[226:229], v[210:213], v[4:7]
	v_mfma_f32_16x16x32_bf16 v[52:55], v[222:225], v[190:193], v[52:55]
	v_mfma_f32_16x16x32_bf16 v[56:59], v[230:233], v[190:193], v[56:59]
	v_mfma_f32_16x16x32_bf16 v[36:39], v[222:225], v[198:201], v[36:39]
	v_mfma_f32_16x16x32_bf16 v[40:43], v[230:233], v[198:201], v[40:43]
	v_mfma_f32_16x16x32_bf16 v[20:23], v[222:225], v[206:209], v[20:23]
	v_mfma_f32_16x16x32_bf16 v[24:27], v[230:233], v[206:209], v[24:27]
	v_mfma_f32_16x16x32_bf16 v[8:11], v[222:225], v[214:217], v[8:11]
	v_mfma_f32_16x16x32_bf16 v[4:7], v[230:233], v[214:217], v[4:7]
	s_add_i32 s55, 0, 0x18000
	v_add_u32_e32 v157, s55, v140
	v_add_u32_e32 v242, s55, v241
	s_barrier
	ds_read_b128 v[144:147], v157
	ds_read_b128 v[162:165], v242
	ds_read_b128 v[166:169], v157 offset:2048
	ds_read_b128 v[170:173], v242 offset:2048
	s_add_u32 s22, s22, 0x80000
	s_addc_u32 s23, s23, 0
	s_mov_b32 m0, s41
	v_lshl_add_u64 v[218:219], s[22:23], 0, v[134:135]
	ds_read_b128 v[174:177], v143 offset:32768
	ds_read_b128 v[190:193], v240 offset:32768
	ds_read_b128 v[194:197], v143 offset:34816
	ds_read_b128 v[198:201], v240 offset:34816
	ds_read_b128 v[202:205], v143 offset:36864
	ds_read_b128 v[206:209], v240 offset:36864
	ds_read_b128 v[210:213], v143 offset:38912
	ds_read_b128 v[214:217], v240 offset:38912
	global_load_lds_dwordx4 v[218:219], off
	v_lshl_add_u64 v[218:219], s[22:23], 0, v[132:133]
	s_mov_b32 m0, s42
	s_nop 0
	global_load_lds_dwordx4 v[218:219], off
	s_waitcnt lgkmcnt(8)
	s_barrier
	s_waitcnt lgkmcnt(0)
	s_waitcnt lgkmcnt(0)
	v_mfma_f32_16x16x32_bf16 v[124:127], v[144:147], v[174:177], v[124:127]
	v_mfma_f32_16x16x32_bf16 v[128:131], v[166:169], v[174:177], v[128:131]
	v_mfma_f32_16x16x32_bf16 v[108:111], v[144:147], v[194:197], v[108:111]
	v_mfma_f32_16x16x32_bf16 v[112:115], v[166:169], v[194:197], v[112:115]
	v_mfma_f32_16x16x32_bf16 v[92:95], v[144:147], v[202:205], v[92:95]
	v_mfma_f32_16x16x32_bf16 v[96:99], v[166:169], v[202:205], v[96:99]
	v_mfma_f32_16x16x32_bf16 v[76:79], v[144:147], v[210:213], v[76:79]
	v_mfma_f32_16x16x32_bf16 v[80:83], v[166:169], v[210:213], v[80:83]
	v_mfma_f32_16x16x32_bf16 v[124:127], v[162:165], v[190:193], v[124:127]
	v_mfma_f32_16x16x32_bf16 v[128:131], v[170:173], v[190:193], v[128:131]
	v_mfma_f32_16x16x32_bf16 v[108:111], v[162:165], v[198:201], v[108:111]
	v_mfma_f32_16x16x32_bf16 v[112:115], v[170:173], v[198:201], v[112:115]
	v_mfma_f32_16x16x32_bf16 v[92:95], v[162:165], v[206:209], v[92:95]
	v_mfma_f32_16x16x32_bf16 v[96:99], v[170:173], v[206:209], v[96:99]
	v_mfma_f32_16x16x32_bf16 v[76:79], v[162:165], v[214:217], v[76:79]
	v_mfma_f32_16x16x32_bf16 v[80:83], v[170:173], v[214:217], v[80:83]
	s_barrier
	s_add_i32 s22, 0, 0x1c000
	s_add_i32 s23, s55, s38
	v_add_u32_e32 v157, s22, v140
	v_add_u32_e32 v242, s22, v241
	v_lshl_add_u64 v[178:179], v[178:179], 0, s[30:31]
	s_mov_b32 m0, s23
	ds_read_b128 v[218:221], v157
	ds_read_b128 v[222:225], v242
	ds_read_b128 v[226:229], v157 offset:2048
	ds_read_b128 v[230:233], v242 offset:2048
	global_load_lds_dwordx4 v[178:179], off
	v_lshl_add_u64 v[178:179], v[234:235], 0, s[30:31]
	s_add_i32 m0, s23, 0x2000
	s_nop 0
	global_load_lds_dwordx4 v[178:179], off
	s_barrier
	s_waitcnt lgkmcnt(0)
	s_waitcnt lgkmcnt(0)
	v_mfma_f32_16x16x32_bf16 v[116:119], v[218:221], v[174:177], v[116:119]
	v_mfma_f32_16x16x32_bf16 v[120:123], v[226:229], v[174:177], v[120:123]
	v_mfma_f32_16x16x32_bf16 v[100:103], v[218:221], v[194:197], v[100:103]
	v_mfma_f32_16x16x32_bf16 v[104:107], v[226:229], v[194:197], v[104:107]
	v_mfma_f32_16x16x32_bf16 v[84:87], v[218:221], v[202:205], v[84:87]
	v_mfma_f32_16x16x32_bf16 v[88:91], v[226:229], v[202:205], v[88:91]
	v_mfma_f32_16x16x32_bf16 v[68:71], v[218:221], v[210:213], v[68:71]
	v_mfma_f32_16x16x32_bf16 v[72:75], v[226:229], v[210:213], v[72:75]
	v_mfma_f32_16x16x32_bf16 v[116:119], v[222:225], v[190:193], v[116:119]
	v_mfma_f32_16x16x32_bf16 v[120:123], v[230:233], v[190:193], v[120:123]
	v_mfma_f32_16x16x32_bf16 v[100:103], v[222:225], v[198:201], v[100:103]
	v_mfma_f32_16x16x32_bf16 v[104:107], v[230:233], v[198:201], v[104:107]
	v_mfma_f32_16x16x32_bf16 v[84:87], v[222:225], v[206:209], v[84:87]
	v_mfma_f32_16x16x32_bf16 v[88:91], v[230:233], v[206:209], v[88:91]
	v_mfma_f32_16x16x32_bf16 v[68:71], v[222:225], v[214:217], v[68:71]
	v_mfma_f32_16x16x32_bf16 v[72:75], v[230:233], v[214:217], v[72:75]
	s_mov_b32 m0, s43
	v_lshl_add_u64 v[178:179], v[236:237], 0, s[30:31]
	s_barrier
	ds_read_b128 v[174:177], v143 offset:49152
	ds_read_b128 v[190:193], v240 offset:49152
	ds_read_b128 v[194:197], v143 offset:51200
	ds_read_b128 v[198:201], v240 offset:51200
	ds_read_b128 v[202:205], v143 offset:53248
	ds_read_b128 v[206:209], v240 offset:53248
	ds_read_b128 v[210:213], v143 offset:55296
	ds_read_b128 v[214:217], v240 offset:55296
	global_load_lds_dwordx4 v[178:179], off
	v_lshl_add_u64 v[178:179], v[238:239], 0, s[30:31]
	s_mov_b32 m0, s46
	s_nop 0
	global_load_lds_dwordx4 v[178:179], off
	s_barrier
; #define PG8_STAGE(bufoff, gbase, voff) do { _Pragma("unroll") for (int _i = 0; _i < 2; ++_i) \
;         __builtin_amdgcn_global_load_lds((const unsigned*)((const char*)(gbase) + (voff)[_i]), (LAS unsigned*)(lds + (bufoff) + ldsw + _i * 8192), 16, 0, 0); } while (0)
; #define PG8_WAIT_V(n) asm volatile("s_waitcnt vmcnt(" #n ")" ::: "memory")
; #define PG8_WAIT_L(n) asm volatile("s_waitcnt lgkmcnt(" #n ")" ::: "memory")
; #define PG8_BAR __builtin_amdgcn_s_barrier()
; #define PG8_SCHED __builtin_amdgcn_sched_barrier(0)
; template <class Epi>
; __device__ __forceinline__ void gemm_phase(LAS unsigned char* lds, const Gemm g, const StaticOrder& S, const Epi& E, const int tid) {
;     ...
;             PG8_BAR; PG8_WAIT_L(0); PG8_MMA(1, 0, At, B0); PG8_BAR; PG8_SCHED;
;             PG8_STAGE(PG8_SB(1, 1), b3 + hstepB, voffB);
;             PG8_WAIT_V(6); PG8_BAR; PG8_MMA(1, 1, At, B1); PG8_BAR;
;         }
;     __device__ __forceinline__ void operator()(f32x4 (&acc)[2][2][4][2], const pg8::Unit& u, int wr, int wc, int fr, int fq) const {
;         const bool hi = fr >= 8;
;         const int row0 = u.pm * 256 + wr * 64 + (fr & 7), col = u.pn * 256 + wc * 64 + fq * 8 + (hi ? 32 : 0);
; #pragma unroll
;         for (int ai = 0; ai < 2; ++ai)
; #pragma unroll
;             for (int m = 0; m < 4; ++m) {
;                 const h8 x0 = pack8(acc[ai][0][m][0], acc[ai][0][m][1]), x1 = pack8(acc[ai][1][m][0], acc[ai][1][m][1]);
;                 const i32x4 snd = hi ? __builtin_bit_cast(i32x4, x0) : __builtin_bit_cast(i32x4, x1);
;                 i32x4 rcv;
; #pragma unroll
;                 for (int d = 0; d < 4; ++d) rcv[d] = __builtin_amdgcn_update_dpp(0, snd[d], 0x128  , 0xF, 0xF, false);
;                 const h8 rv = __builtin_bit_cast(h8, rcv);
;                 const h8 vA = hi ? rv : x0;
;                 const h8 vB = hi ? x1 : rv;
;                 half_t* rowp = O + (size_t)(row0 + ai * 128 + m * 16) * NIN + col;
;                 __builtin_nontemporal_store(vA, (h8*)rowp); __builtin_nontemporal_store(vB, (h8*)(rowp + (size_t)8 * NIN)); }
	s_waitcnt lgkmcnt(0)
	s_waitcnt lgkmcnt(0)
	v_mfma_f32_16x16x32_bf16 v[60:63], v[144:147], v[174:177], v[60:63]
	v_mfma_f32_16x16x32_bf16 v[64:67], v[166:169], v[174:177], v[64:67]
	v_mfma_f32_16x16x32_bf16 v[44:47], v[144:147], v[194:197], v[44:47]
	v_mfma_f32_16x16x32_bf16 v[48:51], v[166:169], v[194:197], v[48:51]
	v_mfma_f32_16x16x32_bf16 v[28:31], v[144:147], v[202:205], v[28:31]
	v_mfma_f32_16x16x32_bf16 v[32:35], v[166:169], v[202:205], v[32:35]
	v_mfma_f32_16x16x32_bf16 v[12:15], v[144:147], v[210:213], v[12:15]
	v_mfma_f32_16x16x32_bf16 v[16:19], v[166:169], v[210:213], v[16:19]
	v_mfma_f32_16x16x32_bf16 v[60:63], v[162:165], v[190:193], v[60:63]
	v_mfma_f32_16x16x32_bf16 v[64:67], v[170:173], v[190:193], v[64:67]
	v_mfma_f32_16x16x32_bf16 v[44:47], v[162:165], v[198:201], v[44:47]
	v_mfma_f32_16x16x32_bf16 v[48:51], v[170:173], v[198:201], v[48:51]
	v_mfma_f32_16x16x32_bf16 v[28:31], v[162:165], v[206:209], v[28:31]
	v_mfma_f32_16x16x32_bf16 v[32:35], v[170:173], v[206:209], v[32:35]
	v_mfma_f32_16x16x32_bf16 v[12:15], v[162:165], v[214:217], v[12:15]
	v_mfma_f32_16x16x32_bf16 v[16:19], v[170:173], v[214:217], v[16:19]
	s_barrier
	s_add_u32 s18, s18, 0x20080
	s_addc_u32 s19, s19, 0
	s_add_i32 s22, s22, s38
	v_lshl_add_u64 v[144:145], s[18:19], 0, v[2:3]
	s_mov_b32 m0, s22
	s_nop 0
	global_load_lds_dwordx4 v[144:145], off
	v_lshl_add_u64 v[144:145], s[18:19], 0, v[0:1]
	s_add_i32 m0, s22, 0x2000
	s_nop 0
	global_load_lds_dwordx4 v[144:145], off
	s_waitcnt vmcnt(6)
	s_barrier
	v_mfma_f32_16x16x32_bf16 v[52:55], v[218:221], v[174:177], v[52:55]
	v_mfma_f32_16x16x32_bf16 v[56:59], v[226:229], v[174:177], v[56:59]
	v_mfma_f32_16x16x32_bf16 v[36:39], v[218:221], v[194:197], v[36:39]
	v_mfma_f32_16x16x32_bf16 v[40:43], v[226:229], v[194:197], v[40:43]
	v_mfma_f32_16x16x32_bf16 v[20:23], v[218:221], v[202:205], v[20:23]
	v_mfma_f32_16x16x32_bf16 v[24:27], v[226:229], v[202:205], v[24:27]
	v_mfma_f32_16x16x32_bf16 v[8:11], v[218:221], v[210:213], v[8:11]
	v_mfma_f32_16x16x32_bf16 v[4:7], v[226:229], v[210:213], v[4:7]
	v_mfma_f32_16x16x32_bf16 v[52:55], v[222:225], v[190:193], v[52:55]
	v_mfma_f32_16x16x32_bf16 v[56:59], v[230:233], v[190:193], v[56:59]
	v_mfma_f32_16x16x32_bf16 v[36:39], v[222:225], v[198:201], v[36:39]
	v_mfma_f32_16x16x32_bf16 v[40:43], v[230:233], v[198:201], v[40:43]
	v_mfma_f32_16x16x32_bf16 v[20:23], v[222:225], v[206:209], v[20:23]
	v_mfma_f32_16x16x32_bf16 v[24:27], v[230:233], v[206:209], v[24:27]
	v_mfma_f32_16x16x32_bf16 v[8:11], v[222:225], v[214:217], v[8:11]
	v_mfma_f32_16x16x32_bf16 v[4:7], v[230:233], v[214:217], v[4:7]
	s_add_i32 s54, s54, 2
	s_add_u32 s14, s14, 0x100
	s_addc_u32 s15, s15, 0
	s_add_u32 s52, s52, 0x100
	s_addc_u32 s53, s53, 0
	s_cmp_gt_u32 s54, 29
	s_barrier
	s_cbranch_scc0 .LBB0_332
	v_cvt_pk_f16_f32 v124, v124, v125
	v_cvt_pk_f16_f32 v116, v116, v117
	v_cvt_pk_f16_f32 v130, v130, v131
	v_cvt_pk_f16_f32 v131, v122, v123
	v_cvt_pk_f16_f32 v128, v128, v129
	v_cvt_pk_f16_f32 v129, v120, v121
	v_cvt_pk_f16_f32 v121, v126, v127
	v_cvt_pk_f16_f32 v118, v118, v119
	v_cndmask_b32_e64 v117, v116, v124, s[4:5]
	v_mov_b32_e32 v147, v3
	v_cndmask_b32_e64 v122, v131, v130, s[4:5]
	v_cndmask_b32_e64 v119, v118, v121, s[4:5]
	v_mov_b32_dpp v147, v117 row_ror:8 row_mask:0xf bank_mask:0xf
	v_mov_b32_e32 v117, v3
	v_mov_b32_e32 v125, v3
	v_lshl_or_b32 v144, s48, 8, v142
	v_cndmask_b32_e64 v120, v129, v128, s[4:5]
	v_mov_b32_dpp v117, v119 row_ror:8 row_mask:0xf bank_mask:0xf
	v_mov_b32_e32 v119, v3
	v_mov_b32_dpp v125, v122 row_ror:8 row_mask:0xf bank_mask:0xf
	v_lshl_add_u32 v146, s49, 8, v141
	v_ashrrev_i32_e32 v145, 31, v144
	v_mov_b32_dpp v119, v120 row_ror:8 row_mask:0xf bank_mask:0xf
	v_cndmask_b32_e64 v123, v130, v125, s[4:5]
	v_cndmask_b32_e64 v121, v121, v117, s[4:5]
	v_cndmask_b32_e64 v120, v124, v147, s[4:5]
	v_cndmask_b32_e64 v127, v125, v131, s[4:5]
	v_cndmask_b32_e64 v125, v117, v118, s[4:5]
	v_cndmask_b32_e64 v124, v147, v116, s[4:5]
	v_mov_b64_e32 v[116:117], s[36:37]
	v_cndmask_b32_e64 v122, v128, v119, s[4:5]
	v_cndmask_b32_e64 v126, v119, v129, s[4:5]
	v_mad_i64_i32 v[128:129], s[14:15], v146, s35, v[116:117]
	v_lshlrev_b64 v[118:119], 1, v[144:145]
	v_lshl_add_u64 v[128:129], v[128:129], 0, v[118:119]
	s_mov_b32 s1, 0x3c000
	global_store_dwordx4 v[128:129], v[120:123], off nt
	v_cvt_pk_f16_f32 v112, v112, v113
	v_cvt_pk_f16_f32 v104, v104, v105
	v_add_co_u32_e32 v120, vcc, s1, v128
	v_cvt_pk_f16_f32 v108, v108, v109
	s_nop 0
	v_addc_co_u32_e32 v121, vcc, 0, v129, vcc
	v_cvt_pk_f16_f32 v109, v100, v101
	global_store_dwordx4 v[120:121], v[124:127], off nt
	v_cvt_pk_f16_f32 v114, v114, v115
	v_cvt_pk_f16_f32 v106, v106, v107
	v_cndmask_b32_e64 v105, v104, v112, s[4:5]
	v_cndmask_b32_e64 v100, v109, v108, s[4:5]
	v_mov_b32_e32 v113, v3
	v_mov_b32_e32 v120, v3
	v_cndmask_b32_e64 v107, v106, v114, s[4:5]
	v_cvt_pk_f16_f32 v110, v110, v111
	v_cvt_pk_f16_f32 v111, v102, v103
	v_mov_b32_dpp v113, v100 row_ror:8 row_mask:0xf bank_mask:0xf
	v_mov_b32_dpp v120, v105 row_ror:8 row_mask:0xf bank_mask:0xf
	v_mov_b32_e32 v105, v3
	v_cndmask_b32_e64 v102, v111, v110, s[4:5]
	v_mov_b32_e32 v115, v3
	v_mov_b32_dpp v105, v107 row_ror:8 row_mask:0xf bank_mask:0xf
	v_cndmask_b32_e64 v100, v108, v113, s[4:5]
	v_or_b32_e32 v108, 16, v146
	v_mov_b32_dpp v115, v102 row_ror:8 row_mask:0xf bank_mask:0xf
	v_cndmask_b32_e64 v107, v105, v106, s[4:5]
	v_cndmask_b32_e64 v106, v120, v104, s[4:5]
	v_cndmask_b32_e64 v104, v113, v109, s[4:5]
	v_mad_i64_i32 v[108:109], s[14:15], v108, s35, v[116:117]
	v_cndmask_b32_e64 v103, v114, v105, s[4:5]
	v_cndmask_b32_e64 v102, v112, v120, s[4:5]
	v_cndmask_b32_e64 v101, v110, v115, s[4:5]
;     __device__ __forceinline__ void operator()(f32x4 (&acc)[2][2][4][2], const pg8::Unit& u, int wr, int wc, int fr, int fq) const {
;         const bool hi = fr >= 8;
;         const int row0 = u.pm * 256 + wr * 64 + (fr & 7), col = u.pn * 256 + wc * 64 + fq * 8 + (hi ? 32 : 0);
; #pragma unroll
;         for (int ai = 0; ai < 2; ++ai)
; #pragma unroll
;             for (int m = 0; m < 4; ++m) {
;                 const h8 x0 = pack8(acc[ai][0][m][0], acc[ai][0][m][1]), x1 = pack8(acc[ai][1][m][0], acc[ai][1][m][1]);
;                 const i32x4 snd = hi ? __builtin_bit_cast(i32x4, x0) : __builtin_bit_cast(i32x4, x1);
;                 i32x4 rcv;
; #pragma unroll
;                 for (int d = 0; d < 4; ++d) rcv[d] = __builtin_amdgcn_update_dpp(0, snd[d], 0x128  , 0xF, 0xF, false);
;                 const h8 rv = __builtin_bit_cast(h8, rcv);
;                 const h8 vA = hi ? rv : x0;
;                 const h8 vB = hi ? x1 : rv;
;                 half_t* rowp = O + (size_t)(row0 + ai * 128 + m * 16) * NIN + col;
;                 __builtin_nontemporal_store(vA, (h8*)rowp); __builtin_nontemporal_store(vB, (h8*)(rowp + (size_t)8 * NIN)); }
	v_lshl_add_u64 v[108:109], v[108:109], 0, v[118:119]
	global_store_dwordx4 v[108:109], v[100:103], off nt
	v_cndmask_b32_e64 v105, v115, v111, s[4:5]
	v_cvt_pk_f16_f32 v96, v96, v97
	v_add_co_u32_e32 v100, vcc, s1, v108
	v_cvt_pk_f16_f32 v88, v88, v89
	s_nop 0
	v_addc_co_u32_e32 v101, vcc, 0, v109, vcc
	v_cvt_pk_f16_f32 v92, v92, v93
	v_cvt_pk_f16_f32 v93, v84, v85
	global_store_dwordx4 v[100:101], v[104:107], off nt
	v_cvt_pk_f16_f32 v98, v98, v99
	v_cvt_pk_f16_f32 v90, v90, v91
	v_cndmask_b32_e64 v89, v88, v96, s[4:5]
	v_cndmask_b32_e64 v84, v93, v92, s[4:5]
	v_mov_b32_e32 v97, v3
	v_mov_b32_e32 v100, v3
	v_cndmask_b32_e64 v91, v90, v98, s[4:5]
	v_cvt_pk_f16_f32 v94, v94, v95
	v_cvt_pk_f16_f32 v95, v86, v87
	v_mov_b32_dpp v97, v84 row_ror:8 row_mask:0xf bank_mask:0xf
	v_mov_b32_dpp v100, v89 row_ror:8 row_mask:0xf bank_mask:0xf
	v_mov_b32_e32 v89, v3
	v_cndmask_b32_e64 v86, v95, v94, s[4:5]
	v_mov_b32_e32 v99, v3
	v_mov_b32_dpp v89, v91 row_ror:8 row_mask:0xf bank_mask:0xf
	v_cndmask_b32_e64 v84, v92, v97, s[4:5]
	v_or_b32_e32 v92, 32, v146
	v_mov_b32_dpp v99, v86 row_ror:8 row_mask:0xf bank_mask:0xf
	v_cndmask_b32_e64 v91, v89, v90, s[4:5]
	v_cndmask_b32_e64 v90, v100, v88, s[4:5]
	v_cndmask_b32_e64 v88, v97, v93, s[4:5]
	v_mad_i64_i32 v[92:93], s[14:15], v92, s35, v[116:117]
	v_cndmask_b32_e64 v87, v98, v89, s[4:5]
	v_cndmask_b32_e64 v86, v96, v100, s[4:5]
	v_cndmask_b32_e64 v85, v94, v99, s[4:5]
	v_lshl_add_u64 v[92:93], v[92:93], 0, v[118:119]
	global_store_dwordx4 v[92:93], v[84:87], off nt
	v_cndmask_b32_e64 v89, v99, v95, s[4:5]
	v_cvt_pk_f16_f32 v80, v80, v81
	v_add_co_u32_e32 v84, vcc, s1, v92
	v_cvt_pk_f16_f32 v72, v72, v73
	s_nop 0
	v_addc_co_u32_e32 v85, vcc, 0, v93, vcc
	v_cvt_pk_f16_f32 v76, v76, v77
	v_cvt_pk_f16_f32 v77, v68, v69
	global_store_dwordx4 v[84:85], v[88:91], off nt
	v_cvt_pk_f16_f32 v82, v82, v83
	v_cvt_pk_f16_f32 v74, v74, v75
	v_cndmask_b32_e64 v73, v72, v80, s[4:5]
	v_cndmask_b32_e64 v68, v77, v76, s[4:5]
	v_mov_b32_e32 v81, v3
	v_mov_b32_e32 v84, v3
	v_cndmask_b32_e64 v75, v74, v82, s[4:5]
	v_cvt_pk_f16_f32 v78, v78, v79
	v_cvt_pk_f16_f32 v79, v70, v71
	v_mov_b32_dpp v81, v68 row_ror:8 row_mask:0xf bank_mask:0xf
	v_mov_b32_dpp v84, v73 row_ror:8 row_mask:0xf bank_mask:0xf
	v_mov_b32_e32 v73, v3
	v_cndmask_b32_e64 v70, v79, v78, s[4:5]
	v_mov_b32_e32 v83, v3
	v_mov_b32_dpp v73, v75 row_ror:8 row_mask:0xf bank_mask:0xf
	v_cndmask_b32_e64 v68, v76, v81, s[4:5]
	v_or_b32_e32 v76, 48, v146
	v_mov_b32_dpp v83, v70 row_ror:8 row_mask:0xf bank_mask:0xf
	v_cndmask_b32_e64 v75, v73, v74, s[4:5]
	v_cndmask_b32_e64 v74, v84, v72, s[4:5]
	v_cndmask_b32_e64 v72, v81, v77, s[4:5]
	v_mad_i64_i32 v[76:77], s[14:15], v76, s35, v[116:117]
	v_cndmask_b32_e64 v71, v82, v73, s[4:5]
	v_cndmask_b32_e64 v70, v80, v84, s[4:5]
	v_cndmask_b32_e64 v69, v78, v83, s[4:5]
	v_lshl_add_u64 v[76:77], v[76:77], 0, v[118:119]
	global_store_dwordx4 v[76:77], v[68:71], off nt
	v_cndmask_b32_e64 v73, v83, v79, s[4:5]
	v_cvt_pk_f16_f32 v64, v64, v65
	v_add_co_u32_e32 v68, vcc, s1, v76
	v_cvt_pk_f16_f32 v56, v56, v57
	s_nop 0
	v_addc_co_u32_e32 v69, vcc, 0, v77, vcc
	global_store_dwordx4 v[68:69], v[72:75], off nt
	v_cvt_pk_f16_f32 v66, v66, v67
	v_cvt_pk_f16_f32 v58, v58, v59
	v_cndmask_b32_e64 v57, v56, v64, s[4:5]
	v_cvt_pk_f16_f32 v60, v60, v61
	v_cvt_pk_f16_f32 v61, v52, v53
	v_mov_b32_e32 v69, v3
	v_cndmask_b32_e64 v59, v58, v66, s[4:5]
	v_cvt_pk_f16_f32 v62, v62, v63
	v_cvt_pk_f16_f32 v63, v54, v55
	v_cndmask_b32_e64 v52, v61, v60, s[4:5]
	v_mov_b32_e32 v65, v3
	v_mov_b32_dpp v69, v57 row_ror:8 row_mask:0xf bank_mask:0xf
	v_mov_b32_e32 v57, v3
	v_add_u32_e32 v68, 0x80, v146
	v_cndmask_b32_e64 v54, v63, v62, s[4:5]
	v_mov_b32_dpp v65, v52 row_ror:8 row_mask:0xf bank_mask:0xf
	v_mov_b32_e32 v67, v3
	v_mov_b32_dpp v57, v59 row_ror:8 row_mask:0xf bank_mask:0xf
	v_cndmask_b32_e64 v52, v60, v65, s[4:5]
	v_mov_b32_dpp v67, v54 row_ror:8 row_mask:0xf bank_mask:0xf
	v_cndmask_b32_e64 v59, v57, v58, s[4:5]
	v_cndmask_b32_e64 v58, v69, v56, s[4:5]
	v_cndmask_b32_e64 v56, v65, v61, s[4:5]
	v_mad_i64_i32 v[60:61], s[14:15], v68, s35, v[116:117]
	v_cndmask_b32_e64 v55, v66, v57, s[4:5]
	v_cndmask_b32_e64 v54, v64, v69, s[4:5]
	v_cndmask_b32_e64 v53, v62, v67, s[4:5]
	v_lshl_add_u64 v[60:61], v[60:61], 0, v[118:119]
	global_store_dwordx4 v[60:61], v[52:55], off nt
	v_cndmask_b32_e64 v57, v67, v63, s[4:5]
	v_cvt_pk_f16_f32 v48, v48, v49
	v_add_co_u32_e32 v52, vcc, s1, v60
	v_cvt_pk_f16_f32 v40, v40, v41
	s_nop 0
	v_addc_co_u32_e32 v53, vcc, 0, v61, vcc
	v_cvt_pk_f16_f32 v44, v44, v45
; #define PG8_WAIT_V(n) asm volatile("s_waitcnt vmcnt(" #n ")" ::: "memory")
; #define PG8_BAR __builtin_amdgcn_s_barrier()
; template <class Epi>
; __device__ __forceinline__ void gemm_phase(LAS unsigned char* lds, const Gemm g, const StaticOrder& S, const Epi& E, const int tid) {
;     ...
;         E(acc, cur, wr, wc, fr, fq);
;         if (!has_next) break;
; #pragma unroll
;         for (int a = 0; a < 2; ++a)
; #pragma unroll
;             for (int b = 0; b < 2; ++b)
; #pragma unroll
;                 for (int m = 0; m < 4; ++m)
; #pragma unroll
;                     for (int n = 0; n < 2; ++n) acc[a][b][m][n] = (f32x4){0.f, 0.f, 0.f, 0.f};
;         cur = nxt; cA = nA; cB = nB; ++ui;
;     }
;     PG8_WAIT_V(0);
;     if (wr == 0) PG8_BAR;
;     PG8_BAR;
;     __device__ __forceinline__ void operator()(f32x4 (&acc)[2][2][4][2], const pg8::Unit& u, int wr, int wc, int fr, int fq) const {
;         const bool hi = fr >= 8;
;         const int row0 = u.pm * 256 + wr * 64 + (fr & 7), col = u.pn * 256 + wc * 64 + fq * 8 + (hi ? 32 : 0);
; #pragma unroll
;         for (int ai = 0; ai < 2; ++ai)
; #pragma unroll
;             for (int m = 0; m < 4; ++m) {
;                 const h8 x0 = pack8(acc[ai][0][m][0], acc[ai][0][m][1]), x1 = pack8(acc[ai][1][m][0], acc[ai][1][m][1]);
;                 const i32x4 snd = hi ? __builtin_bit_cast(i32x4, x0) : __builtin_bit_cast(i32x4, x1);
;                 i32x4 rcv;
; #pragma unroll
;                 for (int d = 0; d < 4; ++d) rcv[d] = __builtin_amdgcn_update_dpp(0, snd[d], 0x128  , 0xF, 0xF, false);
;                 const h8 rv = __builtin_bit_cast(h8, rcv);
;                 const h8 vA = hi ? rv : x0;
;                 const h8 vB = hi ? x1 : rv;
;                 half_t* rowp = O + (size_t)(row0 + ai * 128 + m * 16) * NIN + col;
;                 __builtin_nontemporal_store(vA, (h8*)rowp); __builtin_nontemporal_store(vB, (h8*)(rowp + (size_t)8 * NIN)); }
	v_cvt_pk_f16_f32 v45, v36, v37
	global_store_dwordx4 v[52:53], v[56:59], off nt
	v_cvt_pk_f16_f32 v50, v50, v51
	v_cvt_pk_f16_f32 v42, v42, v43
	v_cndmask_b32_e64 v41, v40, v48, s[4:5]
	v_cndmask_b32_e64 v36, v45, v44, s[4:5]
	v_mov_b32_e32 v49, v3
	v_mov_b32_e32 v52, v3
	v_cndmask_b32_e64 v43, v42, v50, s[4:5]
	v_cvt_pk_f16_f32 v46, v46, v47
	v_cvt_pk_f16_f32 v47, v38, v39
	v_mov_b32_dpp v49, v36 row_ror:8 row_mask:0xf bank_mask:0xf
	v_mov_b32_dpp v52, v41 row_ror:8 row_mask:0xf bank_mask:0xf
	v_mov_b32_e32 v41, v3
	v_cndmask_b32_e64 v38, v47, v46, s[4:5]
	v_mov_b32_e32 v51, v3
	v_mov_b32_dpp v41, v43 row_ror:8 row_mask:0xf bank_mask:0xf
	v_cndmask_b32_e64 v36, v44, v49, s[4:5]
	v_add_u32_e32 v44, 0x90, v146
	v_mov_b32_dpp v51, v38 row_ror:8 row_mask:0xf bank_mask:0xf
	v_cndmask_b32_e64 v43, v41, v42, s[4:5]
	v_cndmask_b32_e64 v42, v52, v40, s[4:5]
	v_cndmask_b32_e64 v40, v49, v45, s[4:5]
	v_mad_i64_i32 v[44:45], s[14:15], v44, s35, v[116:117]
	v_cndmask_b32_e64 v39, v50, v41, s[4:5]
	v_cndmask_b32_e64 v38, v48, v52, s[4:5]
	v_cndmask_b32_e64 v37, v46, v51, s[4:5]
	v_lshl_add_u64 v[44:45], v[44:45], 0, v[118:119]
	global_store_dwordx4 v[44:45], v[36:39], off nt
	v_cndmask_b32_e64 v41, v51, v47, s[4:5]
	v_cvt_pk_f16_f32 v32, v32, v33
	v_add_co_u32_e32 v36, vcc, s1, v44
	v_cvt_pk_f16_f32 v24, v24, v25
	s_nop 0
	v_addc_co_u32_e32 v37, vcc, 0, v45, vcc
	v_cvt_pk_f16_f32 v28, v28, v29
	v_cvt_pk_f16_f32 v29, v20, v21
	global_store_dwordx4 v[36:37], v[40:43], off nt
	v_cvt_pk_f16_f32 v34, v34, v35
	v_cvt_pk_f16_f32 v26, v26, v27
	v_cndmask_b32_e64 v25, v24, v32, s[4:5]
	v_cndmask_b32_e64 v20, v29, v28, s[4:5]
	v_mov_b32_e32 v33, v3
	v_mov_b32_e32 v36, v3
	v_cndmask_b32_e64 v27, v26, v34, s[4:5]
	v_cvt_pk_f16_f32 v30, v30, v31
	v_cvt_pk_f16_f32 v31, v22, v23
	v_mov_b32_dpp v33, v20 row_ror:8 row_mask:0xf bank_mask:0xf
	v_mov_b32_dpp v36, v25 row_ror:8 row_mask:0xf bank_mask:0xf
	v_mov_b32_e32 v25, v3
	v_cvt_pk_f16_f32 v16, v16, v17
	v_cvt_pk_f16_f32 v17, v4, v5
	v_cvt_pk_f16_f32 v5, v14, v15
	v_cvt_pk_f16_f32 v14, v10, v11
	v_cvt_pk_f16_f32 v10, v12, v13
	v_cvt_pk_f16_f32 v8, v8, v9
	v_cndmask_b32_e64 v22, v31, v30, s[4:5]
	v_mov_b32_e32 v35, v3
	v_mov_b32_dpp v25, v27 row_ror:8 row_mask:0xf bank_mask:0xf
	v_cndmask_b32_e64 v20, v28, v33, s[4:5]
	v_add_u32_e32 v28, 0xa0, v146
	v_cndmask_b32_e64 v9, v8, v10, s[4:5]
	v_mov_b32_e32 v12, v3
	v_mov_b32_dpp v35, v22 row_ror:8 row_mask:0xf bank_mask:0xf
	v_cndmask_b32_e64 v27, v25, v26, s[4:5]
	v_cndmask_b32_e64 v26, v36, v24, s[4:5]
	v_cndmask_b32_e64 v24, v33, v29, s[4:5]
	v_mad_i64_i32 v[28:29], s[14:15], v28, s35, v[116:117]
	v_cvt_pk_f16_f32 v18, v18, v19
	v_cvt_pk_f16_f32 v19, v6, v7
	v_cndmask_b32_e64 v4, v17, v16, s[4:5]
	v_mov_b32_dpp v12, v9 row_ror:8 row_mask:0xf bank_mask:0xf
	v_mov_b32_e32 v13, v3
	v_cndmask_b32_e64 v23, v34, v25, s[4:5]
	v_cndmask_b32_e64 v22, v32, v36, s[4:5]
	v_cndmask_b32_e64 v21, v30, v35, s[4:5]
	v_lshl_add_u64 v[28:29], v[28:29], 0, v[118:119]
	v_cndmask_b32_e64 v6, v19, v18, s[4:5]
	v_cndmask_b32_e64 v7, v14, v5, s[4:5]
	v_mov_b32_e32 v9, v3
	v_mov_b32_dpp v13, v4 row_ror:8 row_mask:0xf bank_mask:0xf
	v_mov_b32_e32 v11, v3
	v_cndmask_b32_e64 v4, v10, v12, s[4:5]
	v_cndmask_b32_e64 v8, v12, v8, s[4:5]
	v_add_u32_e32 v12, 0xb0, v146
	global_store_dwordx4 v[28:29], v[20:23], off nt
	v_mov_b32_dpp v9, v7 row_ror:8 row_mask:0xf bank_mask:0xf
	v_mov_b32_dpp v11, v6 row_ror:8 row_mask:0xf bank_mask:0xf
	v_add_co_u32_e32 v20, vcc, s1, v28
	v_cndmask_b32_e64 v6, v16, v13, s[4:5]
	v_cndmask_b32_e64 v10, v13, v17, s[4:5]
	v_mad_i64_i32 v[12:13], s[14:15], v12, s35, v[116:117]
	v_addc_co_u32_e32 v21, vcc, 0, v29, vcc
	v_cndmask_b32_e64 v7, v18, v11, s[4:5]
	v_cndmask_b32_e64 v5, v5, v9, s[4:5]
	v_lshl_add_u64 v[12:13], v[12:13], 0, v[118:119]
	global_store_dwordx4 v[12:13], v[4:7], off nt
	v_cndmask_b32_e64 v25, v35, v31, s[4:5]
	v_cndmask_b32_e64 v11, v11, v19, s[4:5]
	v_add_co_u32_e32 v4, vcc, 0x3c000, v12
	v_cndmask_b32_e64 v9, v9, v14, s[4:5]
	s_nop 0
	v_addc_co_u32_e32 v5, vcc, 0, v13, vcc
	s_and_b64 vcc, exec, s[6:7]
	s_mov_b32 s48, s0
	s_mov_b32 s49, s8
	s_mov_b64 s[18:19], s[12:13]
	s_mov_b64 s[14:15], s[10:11]
	global_store_dwordx4 v[20:21], v[24:27], off nt
	global_store_dwordx4 v[4:5], v[8:11], off nt
	s_cbranch_vccz .LBB0_329
	s_waitcnt vmcnt(0)
	v_readlane_b32 s42, v251, 7
	v_readlane_b32 s46, v251, 9
	v_readlane_b32 s48, v251, 13
	s_cmpk_gt_u32 s20, 0xff
	v_readlane_b32 s43, v251, 8
	v_readlane_b32 s47, v251, 10
	v_readlane_b32 s49, v251, 14
	s_cbranch_scc1 .LBB0_336
	s_barrier
